# GEMM tile prologues zero accumulators with 64-bit moves; DA bias table loaded once per workgroup; residual epilogue loads issued per token group
# speedup vs baseline: 1.0189x; 1.0106x over previous
; #define STAGE(P, BASE, br, kt) do { int _so = ((br) * K + (kt) * BK) * 2; \
;     __builtin_amdgcn_raw_ptr_buffer_load_lds(rs_##BASE, (__attribute__((address_space(3))) void*)((char*)(P) + tx * 16), 16, voff0, _so, 0, 0); \
;     __builtin_amdgcn_raw_ptr_buffer_load_lds(rs_##BASE, (__attribute__((address_space(3))) void*)((char*)(P) + tx * 16 + 8192), 16, voff1, _so, 0, 0); } while (0)
; #define WAIT_V(n) asm volatile("s_waitcnt vmcnt(" #n ")" ::: "memory")
; #define BAR __builtin_amdgcn_s_barrier()
; template <class Epi> ...
;     ...
;   f32x4 acc[2][2][4][2] = {};
;   bf16x8 At[4][2], B0[2][2], B1[2][2];
;   int nt = K / BK;
;   int voff0, voff1;
;   { int _r, _c; stage_rc(tx * 16, _r, _c); voff0 = (_r * K + _c) * 2; stage_rc(tx * 16 + 8192, _r, _c); voff1 = (_r * K + _c) * 2; }
;   __amdgpu_buffer_rsrc_t rs_A = __builtin_amdgcn_make_buffer_rsrc((void*)A, 0, 0x7fffffff, 0x00020000);
;   __amdgpu_buffer_rsrc_t rs_Bt = __builtin_amdgcn_make_buffer_rsrc((void*)Bt, 0, 0x7fffffff, 0x00020000);
;   if (!pre) {
;     STAGE(SB(0, 0), Bt, bcol, 0); STAGE(SA(0, 0), A, brow, 0);
;     STAGE(SB(0, 1), Bt, bcol + HALF, 0); STAGE(SA(0, 1), A, brow + HALF, 0);
;   }
;   if (wr == 1) BAR;
;   if (pre) { WAIT_V(0); } else { WAIT_V(4); }
;   BAR;
;   STAGE(SB(1, 0), Bt, bcol, 1); STAGE(SA(1, 0), A, brow, 1); STAGE(SB(1, 1), Bt, bcol + HALF, 1);
;   WAIT_V(6); BAR;
.LBB0_73:
	v_readlane_b32 s35, v254, 30
	s_lshl_b32 s20, s34, 11
	s_or_b32 s6, s20, 0x80
	v_add_u32_e32 v146, s35, v0
	v_add_u32_e32 v147, 0x2000, v146
	v_readfirstlane_b32 s7, v146
	s_mov_b32 m0, s7
	v_readfirstlane_b32 s7, v147
	v_add_u32_e32 v148, 0x8000, v136
	s_barrier
	buffer_load_dwordx4 v32, s[76:79], s6 offen lds
	s_mov_b32 m0, s7
	s_lshl_b32 s21, s31, 11
	v_readfirstlane_b32 s34, v148
	v_add_u32_e32 v150, 0xa000, v136
	v_readlane_b32 s36, v254, 31
	buffer_load_dwordx4 v130, s[76:79], s6 offen lds
	s_or_b32 s31, s21, 0x80
	s_mov_b32 s6, s78
	s_mov_b32 s7, s79
	s_mov_b32 m0, s34
	v_readfirstlane_b32 s34, v150
	v_add_u32_e32 v153, s36, v0
	buffer_load_dwordx4 v32, s[4:7], s31 offen lds
	s_mov_b32 m0, s34
	v_readfirstlane_b32 s34, v153
	v_add_u32_e32 v154, 0x2000, v153
	buffer_load_dwordx4 v130, s[4:7], s31 offen lds
	s_add_i32 s31, s20, 0x40080
	s_mov_b32 m0, s34
	v_readfirstlane_b32 s34, v154
	buffer_load_dwordx4 v32, s[76:79], s31 offen lds
	s_mov_b32 m0, s34
	v_and_b32_e32 v2, 15, v133
	buffer_load_dwordx4 v130, s[76:79], s31 offen lds
	v_lshlrev_b32_e32 v0, 6, v2
	v_lshlrev_b32_e32 v2, 2, v133
	v_and_b32_e32 v3, 48, v133
	v_and_b32_e32 v2, 32, v2
	v_bitop3_b32 v0, v0, v2, v3 bitop3:0x36
	s_waitcnt vmcnt(11)
	v_lshlrev_b32_e32 v8, 6, v133
	s_movk_i32 s31, 0x3c0
	s_waitcnt vmcnt(6)
	v_add_u32_e32 v4, s71, v0
	v_add_u32_e32 v5, s73, v0
	v_add_u32_e32 v6, s35, v0
	v_add_u32_e32 v7, s36, v0
	v_lshlrev_b32_e32 v1, 13, v1
	v_add_u32_e32 v10, 0, v0
	v_and_or_b32 v0, v8, s31, v3
	v_and_b32_e32 v9, 0x3000, v8
	v_xad_u32 v2, v0, v2, 0
	v_or_b32_e32 v3, 0x800, v1
	v_or_b32_e32 v8, 0x1000, v1
	v_or_b32_e32 v11, 0x1800, v1
	v_mov_b32_e32 v0, 0
	v_add_u32_e32 v152, 0xc000, v136
	v_add_u32_e32 v151, 0xe000, v136
	v_add_u32_e32 v139, 0x2000, v137
	v_add_u32_e32 v138, 0x2000, v134
	s_mov_b32 s31, -2
	s_mov_b32 s34, 0
	v_add_u32_e32 v155, v4, v9
	v_add_u32_e32 v143, v10, v1
	v_add_u32_e32 v142, v2, v3
	v_add_u32_e32 v141, v2, v8
	v_add_u32_e32 v140, v2, v11
	v_add_u32_e32 v149, v5, v9
	v_add_u32_e32 v145, v6, v9
	v_add_u32_e32 v144, v7, v9
	v_mov_b32_e32 v1, v0
	v_mov_b64_e32 v[2:3], 0
	v_mov_b64_e32 v[4:5], 0
	v_mov_b64_e32 v[6:7], 0
	v_mov_b64_e32 v[8:9], 0
	v_mov_b64_e32 v[10:11], 0
	s_waitcnt vmcnt(10)
	v_mov_b64_e32 v[12:13], 0
	v_mov_b64_e32 v[14:15], 0
	v_mov_b64_e32 v[16:17], 0
	v_mov_b64_e32 v[18:19], 0
	v_mov_b64_e32 v[20:21], 0
	v_mov_b64_e32 v[22:23], 0
	v_mov_b64_e32 v[24:25], 0
	v_mov_b64_e32 v[26:27], 0
	v_mov_b64_e32 v[28:29], 0
	v_mov_b64_e32 v[30:31], 0
	v_mov_b64_e32 v[34:35], 0
	v_mov_b64_e32 v[36:37], 0
	v_mov_b64_e32 v[38:39], 0
	v_mov_b64_e32 v[40:41], 0
	v_mov_b64_e32 v[42:43], 0
	v_mov_b64_e32 v[44:45], 0
	v_mov_b64_e32 v[46:47], 0
	v_mov_b64_e32 v[48:49], 0
	v_mov_b64_e32 v[50:51], 0
	v_mov_b64_e32 v[52:53], 0
	v_mov_b64_e32 v[54:55], 0
	v_mov_b64_e32 v[56:57], 0
	v_mov_b64_e32 v[58:59], 0
	v_mov_b64_e32 v[60:61], 0
	v_mov_b64_e32 v[62:63], 0
	v_mov_b64_e32 v[64:65], 0
	v_mov_b64_e32 v[66:67], 0
	v_mov_b64_e32 v[68:69], 0
	v_mov_b64_e32 v[70:71], 0
	v_mov_b64_e32 v[72:73], 0
	v_mov_b64_e32 v[74:75], 0
	v_mov_b64_e32 v[76:77], 0
	v_mov_b64_e32 v[78:79], 0
	v_mov_b64_e32 v[80:81], 0
	v_mov_b64_e32 v[82:83], 0
	v_mov_b64_e32 v[84:85], 0
	v_mov_b64_e32 v[86:87], 0
	v_mov_b64_e32 v[88:89], 0
	v_mov_b64_e32 v[90:91], 0
	v_mov_b64_e32 v[92:93], 0
	v_mov_b64_e32 v[94:95], 0
	v_mov_b64_e32 v[96:97], 0
	v_mov_b64_e32 v[98:99], 0
	v_mov_b64_e32 v[100:101], 0
	v_mov_b64_e32 v[102:103], 0
	v_mov_b64_e32 v[104:105], 0
	v_mov_b64_e32 v[106:107], 0
	v_mov_b64_e32 v[108:109], 0
	v_mov_b64_e32 v[110:111], 0
	v_mov_b64_e32 v[112:113], 0
	v_mov_b64_e32 v[114:115], 0
	v_mov_b64_e32 v[116:117], 0
	v_mov_b64_e32 v[118:119], 0
	v_mov_b64_e32 v[120:121], 0
	v_mov_b64_e32 v[122:123], 0
	v_mov_b64_e32 v[124:125], 0
	v_mov_b64_e32 v[126:127], 0
	v_mov_b64_e32 v[128:129], 0
	s_barrier

; #define STAGE(P, BASE, br, kt) do { int _so = ((br) * K + (kt) * BK) * 2; \
;     __builtin_amdgcn_raw_ptr_buffer_load_lds(rs_##BASE, (__attribute__((address_space(3))) void*)((char*)(P) + tx * 16), 16, voff0, _so, 0, 0); \
;     __builtin_amdgcn_raw_ptr_buffer_load_lds(rs_##BASE, (__attribute__((address_space(3))) void*)((char*)(P) + tx * 16 + 8192), 16, voff1, _so, 0, 0); } while (0)
; #define WAIT_V(n) asm volatile("s_waitcnt vmcnt(" #n ")" ::: "memory")
; #define BAR __builtin_amdgcn_s_barrier()
; template <class Epi> ...
;     ...
;   int wid = tx >> 6, lane = tx & 63, wr = wid >> 2, wc = wid & 3, fr = lane & 15, fq = lane >> 4;
;   f32x4 acc[2][2][4][2] = {};
;   bf16x8 At[4][2], B0[2][2], B1[2][2];
;   int nt = K / BK;
;   int voff0, voff1;
;   { int _r, _c; stage_rc(tx * 16, _r, _c); voff0 = (_r * K + _c) * 2; stage_rc(tx * 16 + 8192, _r, _c); voff1 = (_r * K + _c) * 2; }
;   __amdgpu_buffer_rsrc_t rs_A = __builtin_amdgcn_make_buffer_rsrc((void*)A, 0, 0x7fffffff, 0x00020000);
;   __amdgpu_buffer_rsrc_t rs_Bt = __builtin_amdgcn_make_buffer_rsrc((void*)Bt, 0, 0x7fffffff, 0x00020000);
;   if (!pre) {
;     STAGE(SB(0, 0), Bt, bcol, 0); STAGE(SA(0, 0), A, brow, 0);
;     STAGE(SB(0, 1), Bt, bcol + HALF, 0); STAGE(SA(0, 1), A, brow + HALF, 0);
;   }
;   if (wr == 1) BAR;
;   if (pre) { WAIT_V(0); } else { WAIT_V(4); }
;   BAR;
;   STAGE(SB(1, 0), Bt, bcol, 1); STAGE(SA(1, 0), A, brow, 1); STAGE(SB(1, 1), Bt, bcol + HALF, 1);
;   WAIT_V(6); BAR;
.LBB0_1656:
	s_or_b64 exec, exec, s[6:7]
	v_readlane_b32 s28, v254, 30
	s_or_b32 s6, s25, 0x80
	v_add_u32_e32 v148, 0x8000, v140
	v_add_u32_e32 v146, s28, v0
	v_add_u32_e32 v147, 0x2000, v146
	v_readfirstlane_b32 s7, v146
	s_mov_b32 m0, s7
	v_readfirstlane_b32 s7, v147
	s_waitcnt vmcnt(4)
	s_barrier
	buffer_load_dwordx4 v134, s[76:79], s6 offen lds
	s_mov_b32 m0, s7
	v_readfirstlane_b32 s27, v148
	v_add_u32_e32 v150, 0xa000, v140
	v_readlane_b32 s29, v254, 31
	buffer_load_dwordx4 v135, s[76:79], s6 offen lds
	s_or_b32 s26, s24, 0x80
	s_mov_b32 s6, s78
	s_mov_b32 s7, s79
	s_mov_b32 m0, s27
	v_readfirstlane_b32 s27, v150
	v_add_u32_e32 v151, s29, v0
	buffer_load_dwordx4 v134, s[4:7], s26 offen lds
	s_mov_b32 m0, s27
	v_readfirstlane_b32 s27, v151
	v_add_u32_e32 v152, 0x2000, v151
	buffer_load_dwordx4 v135, s[4:7], s26 offen lds
	s_or_b32 s26, s25, 0x40080
	s_mov_b32 m0, s27
	v_readfirstlane_b32 s27, v152
	buffer_load_dwordx4 v134, s[76:79], s26 offen lds
	s_mov_b32 m0, s27
	v_and_b32_e32 v2, 15, v32
	buffer_load_dwordx4 v135, s[76:79], s26 offen lds
	v_lshlrev_b32_e32 v0, 6, v2
	v_lshlrev_b32_e32 v2, 2, v32
	v_and_b32_e32 v3, 48, v32
	v_and_b32_e32 v2, 32, v2
	v_bitop3_b32 v0, v0, v2, v3 bitop3:0x36
	v_lshlrev_b32_e32 v8, 6, v32
	s_movk_i32 s26, 0x3c0
	s_waitcnt vmcnt(6)
	v_add_u32_e32 v4, s71, v0
	v_add_u32_e32 v5, s73, v0
	v_add_u32_e32 v6, s28, v0
	v_add_u32_e32 v7, s29, v0
	v_lshlrev_b32_e32 v1, 13, v1
	v_add_u32_e32 v10, 0, v0
	v_and_or_b32 v0, v8, s26, v3
	v_and_b32_e32 v9, 0x3000, v8
	v_xad_u32 v2, v0, v2, 0
	v_or_b32_e32 v3, 0x800, v1
	v_or_b32_e32 v8, 0x1000, v1
	v_or_b32_e32 v11, 0x1800, v1
	v_mov_b32_e32 v0, 0
	s_mov_b32 s26, -2
	s_mov_b32 s27, 0
	v_add_u32_e32 v153, v4, v9
	v_add_u32_e32 v133, v10, v1
	v_add_u32_e32 v132, v2, v3
	v_add_u32_e32 v131, v2, v8
	v_add_u32_e32 v130, v2, v11
	v_add_u32_e32 v149, v5, v9
	v_add_u32_e32 v137, v6, v9
	v_add_u32_e32 v136, v7, v9
	v_mov_b32_e32 v1, v0
	v_mov_b64_e32 v[2:3], 0
	v_mov_b64_e32 v[4:5], 0
	v_mov_b64_e32 v[6:7], 0
	v_mov_b64_e32 v[8:9], 0
	v_mov_b64_e32 v[10:11], 0
	v_mov_b64_e32 v[12:13], 0
	v_mov_b64_e32 v[14:15], 0
	v_mov_b64_e32 v[16:17], 0
	v_mov_b64_e32 v[18:19], 0
	v_mov_b64_e32 v[20:21], 0
	v_mov_b64_e32 v[22:23], 0
	v_mov_b64_e32 v[24:25], 0
	v_mov_b64_e32 v[26:27], 0
	v_mov_b64_e32 v[28:29], 0
	v_mov_b64_e32 v[30:31], 0
	v_mov_b64_e32 v[34:35], 0
	v_mov_b64_e32 v[36:37], 0
	v_mov_b64_e32 v[38:39], 0
	v_mov_b64_e32 v[40:41], 0
	v_mov_b64_e32 v[42:43], 0
	v_mov_b64_e32 v[44:45], 0
	v_mov_b64_e32 v[46:47], 0
	v_mov_b64_e32 v[48:49], 0
	v_mov_b64_e32 v[50:51], 0
	v_mov_b64_e32 v[52:53], 0
	v_mov_b64_e32 v[54:55], 0
	v_mov_b64_e32 v[56:57], 0
	v_mov_b64_e32 v[58:59], 0
	v_mov_b64_e32 v[60:61], 0
	v_mov_b64_e32 v[62:63], 0
	v_mov_b64_e32 v[64:65], 0
	v_mov_b64_e32 v[66:67], 0
	v_mov_b64_e32 v[68:69], 0
	v_mov_b64_e32 v[70:71], 0
	v_mov_b64_e32 v[72:73], 0
	v_mov_b64_e32 v[74:75], 0
	v_mov_b64_e32 v[76:77], 0
	v_mov_b64_e32 v[78:79], 0
	v_mov_b64_e32 v[80:81], 0
	v_mov_b64_e32 v[82:83], 0
	v_mov_b64_e32 v[84:85], 0
	v_mov_b64_e32 v[86:87], 0
	v_mov_b64_e32 v[88:89], 0
	v_mov_b64_e32 v[90:91], 0
	v_mov_b64_e32 v[92:93], 0
	v_mov_b64_e32 v[94:95], 0
	v_mov_b64_e32 v[96:97], 0
	v_mov_b64_e32 v[98:99], 0
	v_mov_b64_e32 v[100:101], 0
	v_mov_b64_e32 v[102:103], 0
	v_mov_b64_e32 v[104:105], 0
	v_mov_b64_e32 v[106:107], 0
	v_mov_b64_e32 v[108:109], 0
	v_mov_b64_e32 v[110:111], 0
	v_mov_b64_e32 v[112:113], 0
	v_mov_b64_e32 v[114:115], 0
	v_mov_b64_e32 v[116:117], 0
	v_mov_b64_e32 v[118:119], 0
	v_mov_b64_e32 v[120:121], 0
	v_mov_b64_e32 v[122:123], 0
	v_mov_b64_e32 v[124:125], 0
	v_mov_b64_e32 v[126:127], 0
	v_mov_b64_e32 v[128:129], 0
	v_add_u32_e32 v155, 0xc000, v140
	v_add_u32_e32 v154, 0xe000, v140
	s_barrier

; #define STAGE(P, BASE, br, kt) do { int _so = ((br) * K + (kt) * BK) * 2; \
;     __builtin_amdgcn_raw_ptr_buffer_load_lds(rs_##BASE, (__attribute__((address_space(3))) void*)((char*)(P) + tx * 16), 16, voff0, _so, 0, 0); \
;     __builtin_amdgcn_raw_ptr_buffer_load_lds(rs_##BASE, (__attribute__((address_space(3))) void*)((char*)(P) + tx * 16 + 8192), 16, voff1, _so, 0, 0); } while (0)
; #define WAIT_V(n) asm volatile("s_waitcnt vmcnt(" #n ")" ::: "memory")
; #define BAR __builtin_amdgcn_s_barrier()
; template <class Epi> ...
;     ...
;   int wid = tx >> 6, lane = tx & 63, wr = wid >> 2, wc = wid & 3, fr = lane & 15, fq = lane >> 4;
;   f32x4 acc[2][2][4][2] = {};
;   bf16x8 At[4][2], B0[2][2], B1[2][2];
;   int nt = K / BK;
;   int voff0, voff1;
;   { int _r, _c; stage_rc(tx * 16, _r, _c); voff0 = (_r * K + _c) * 2; stage_rc(tx * 16 + 8192, _r, _c); voff1 = (_r * K + _c) * 2; }
;   __amdgpu_buffer_rsrc_t rs_A = __builtin_amdgcn_make_buffer_rsrc((void*)A, 0, 0x7fffffff, 0x00020000);
;   __amdgpu_buffer_rsrc_t rs_Bt = __builtin_amdgcn_make_buffer_rsrc((void*)Bt, 0, 0x7fffffff, 0x00020000);
;   if (!pre) {
;     STAGE(SB(0, 0), Bt, bcol, 0); STAGE(SA(0, 0), A, brow, 0);
;     STAGE(SB(0, 1), Bt, bcol + HALF, 0); STAGE(SA(0, 1), A, brow + HALF, 0);
;   }
;   if (wr == 1) BAR;
;   if (pre) { WAIT_V(0); } else { WAIT_V(4); }
;   BAR;
;   STAGE(SB(1, 0), Bt, bcol, 1); STAGE(SA(1, 0), A, brow, 1); STAGE(SB(1, 1), Bt, bcol + HALF, 1);
;   WAIT_V(6); BAR;
.LBB0_1681:
	v_readlane_b32 s29, v254, 30
	s_lshl_b32 s18, s28, 11
	s_or_b32 s6, s18, 0x80
	v_add_u32_e32 v146, s29, v0
	v_add_u32_e32 v147, 0x2000, v146
	v_readfirstlane_b32 s7, v146
	s_mov_b32 m0, s7
	v_readfirstlane_b32 s7, v147
	v_add_u32_e32 v148, 0x8000, v136
	s_barrier
	buffer_load_dwordx4 v32, s[76:79], s6 offen lds
	s_mov_b32 m0, s7
	s_lshl_b32 s19, s27, 11
	v_readfirstlane_b32 s28, v148
	v_add_u32_e32 v150, 0xa000, v136
	v_readlane_b32 s30, v254, 31
	buffer_load_dwordx4 v130, s[76:79], s6 offen lds
	s_or_b32 s27, s19, 0x80
	s_mov_b32 s6, s78
	s_mov_b32 s7, s79
	s_mov_b32 m0, s28
	v_readfirstlane_b32 s28, v150
	v_add_u32_e32 v153, s30, v0
	buffer_load_dwordx4 v32, s[4:7], s27 offen lds
	s_mov_b32 m0, s28
	v_readfirstlane_b32 s28, v153
	v_add_u32_e32 v154, 0x2000, v153
	buffer_load_dwordx4 v130, s[4:7], s27 offen lds
	s_add_i32 s27, s18, 0x40080
	s_mov_b32 m0, s28
	v_readfirstlane_b32 s28, v154
	buffer_load_dwordx4 v32, s[76:79], s27 offen lds
	s_mov_b32 m0, s28
	v_and_b32_e32 v2, 15, v133
	buffer_load_dwordx4 v130, s[76:79], s27 offen lds
	v_lshlrev_b32_e32 v0, 6, v2
	v_lshlrev_b32_e32 v2, 2, v133
	v_and_b32_e32 v3, 48, v133
	v_and_b32_e32 v2, 32, v2
	v_bitop3_b32 v0, v0, v2, v3 bitop3:0x36
	s_waitcnt vmcnt(11)
	v_lshlrev_b32_e32 v8, 6, v133
	s_movk_i32 s27, 0x3c0
	s_waitcnt vmcnt(6)
	v_add_u32_e32 v4, s71, v0
	v_add_u32_e32 v5, s73, v0
	v_add_u32_e32 v6, s29, v0
	v_add_u32_e32 v7, s30, v0
	v_lshlrev_b32_e32 v1, 13, v1
	v_add_u32_e32 v10, 0, v0
	v_and_or_b32 v0, v8, s27, v3
	v_and_b32_e32 v9, 0x3000, v8
	v_xad_u32 v2, v0, v2, 0
	v_or_b32_e32 v3, 0x800, v1
	v_or_b32_e32 v8, 0x1000, v1
	v_or_b32_e32 v11, 0x1800, v1
	v_mov_b32_e32 v0, 0
	v_add_u32_e32 v152, 0xc000, v136
	v_add_u32_e32 v151, 0xe000, v136
	v_add_u32_e32 v139, 0x2000, v137
	v_add_u32_e32 v138, 0x2000, v134
	s_mov_b32 s27, -2
	s_mov_b32 s28, 0
	v_add_u32_e32 v155, v4, v9
	v_add_u32_e32 v143, v10, v1
	v_add_u32_e32 v142, v2, v3
	v_add_u32_e32 v141, v2, v8
	v_add_u32_e32 v140, v2, v11
	v_add_u32_e32 v149, v5, v9
	v_add_u32_e32 v145, v6, v9
	v_add_u32_e32 v144, v7, v9
	v_mov_b32_e32 v1, v0
	v_mov_b64_e32 v[2:3], 0
	v_mov_b64_e32 v[4:5], 0
	v_mov_b64_e32 v[6:7], 0
	v_mov_b64_e32 v[8:9], 0
	v_mov_b64_e32 v[10:11], 0
	s_waitcnt vmcnt(10)
	v_mov_b64_e32 v[12:13], 0
	v_mov_b64_e32 v[14:15], 0
	v_mov_b64_e32 v[16:17], 0
	v_mov_b64_e32 v[18:19], 0
	v_mov_b64_e32 v[20:21], 0
	v_mov_b64_e32 v[22:23], 0
	v_mov_b64_e32 v[24:25], 0
	v_mov_b64_e32 v[26:27], 0
	v_mov_b64_e32 v[28:29], 0
	v_mov_b64_e32 v[30:31], 0
	v_mov_b64_e32 v[34:35], 0
	v_mov_b64_e32 v[36:37], 0
	v_mov_b64_e32 v[38:39], 0
	v_mov_b64_e32 v[40:41], 0
	v_mov_b64_e32 v[42:43], 0
	v_mov_b64_e32 v[44:45], 0
	v_mov_b64_e32 v[46:47], 0
	v_mov_b64_e32 v[48:49], 0
	v_mov_b64_e32 v[50:51], 0
	v_mov_b64_e32 v[52:53], 0
	v_mov_b64_e32 v[54:55], 0
	v_mov_b64_e32 v[56:57], 0
	v_mov_b64_e32 v[58:59], 0
	v_mov_b64_e32 v[60:61], 0
	v_mov_b64_e32 v[62:63], 0
	v_mov_b64_e32 v[64:65], 0
	v_mov_b64_e32 v[66:67], 0
	v_mov_b64_e32 v[68:69], 0
	v_mov_b64_e32 v[70:71], 0
	v_mov_b64_e32 v[72:73], 0
	v_mov_b64_e32 v[74:75], 0
	v_mov_b64_e32 v[76:77], 0
	v_mov_b64_e32 v[78:79], 0
	v_mov_b64_e32 v[80:81], 0
	v_mov_b64_e32 v[82:83], 0
	v_mov_b64_e32 v[84:85], 0
	v_mov_b64_e32 v[86:87], 0
	v_mov_b64_e32 v[88:89], 0
	v_mov_b64_e32 v[90:91], 0
	v_mov_b64_e32 v[92:93], 0
	v_mov_b64_e32 v[94:95], 0
	v_mov_b64_e32 v[96:97], 0
	v_mov_b64_e32 v[98:99], 0
	v_mov_b64_e32 v[100:101], 0
	v_mov_b64_e32 v[102:103], 0
	v_mov_b64_e32 v[104:105], 0
	v_mov_b64_e32 v[106:107], 0
	v_mov_b64_e32 v[108:109], 0
	v_mov_b64_e32 v[110:111], 0
	v_mov_b64_e32 v[112:113], 0
	v_mov_b64_e32 v[114:115], 0
	v_mov_b64_e32 v[116:117], 0
	v_mov_b64_e32 v[118:119], 0
	v_mov_b64_e32 v[120:121], 0
	v_mov_b64_e32 v[122:123], 0
	v_mov_b64_e32 v[124:125], 0
	v_mov_b64_e32 v[126:127], 0
	v_mov_b64_e32 v[128:129], 0
	s_barrier

; __device__ __forceinline__ void diff_attn_phase(const Params& p, int j, int layer_idx, char* shm, int wv) {
;     ...
;     __syncthreads();
;     if (tid < 128) btab[tid] = p.biastab[h * 128 + tid];
.LBB0_1778:
	s_lshl_b32 s6, s28, 7
	s_and_b32 s9, s6, 0x380
	s_barrier
	s_andn2_b64 vcc, s[4:5], s[0:1]
	s_and_saveexec_b64 s[6:7], vcc
	s_cbranch_execz .LBB0_1780
	v_add_u32_e32 v0, s9, v186
	v_ashrrev_i32_e32 v1, 31, v0
	v_lshl_add_u64 v[0:1], v[0:1], 2, s[10:11]
	global_load_dword v0, v[0:1], off
	s_waitcnt vmcnt(0)
	ds_write_b32 v187, v0

; #define STAGE(P, BASE, br, kt) do { int _so = ((br) * K + (kt) * BK) * 2; \
;     __builtin_amdgcn_raw_ptr_buffer_load_lds(rs_##BASE, (__attribute__((address_space(3))) void*)((char*)(P) + tx * 16), 16, voff0, _so, 0, 0); \
;     __builtin_amdgcn_raw_ptr_buffer_load_lds(rs_##BASE, (__attribute__((address_space(3))) void*)((char*)(P) + tx * 16 + 8192), 16, voff1, _so, 0, 0); } while (0)
; #define WAIT_V(n) asm volatile("s_waitcnt vmcnt(" #n ")" ::: "memory")
; #define BAR __builtin_amdgcn_s_barrier()
; template <class Epi> ...
;     ...
;   int wid = tx >> 6, lane = tx & 63, wr = wid >> 2, wc = wid & 3, fr = lane & 15, fq = lane >> 4;
;   f32x4 acc[2][2][4][2] = {};
;   bf16x8 At[4][2], B0[2][2], B1[2][2];
;   int nt = K / BK;
;   int voff0, voff1;
;   { int _r, _c; stage_rc(tx * 16, _r, _c); voff0 = (_r * K + _c) * 2; stage_rc(tx * 16 + 8192, _r, _c); voff1 = (_r * K + _c) * 2; }
;   __amdgpu_buffer_rsrc_t rs_A = __builtin_amdgcn_make_buffer_rsrc((void*)A, 0, 0x7fffffff, 0x00020000);
;   __amdgpu_buffer_rsrc_t rs_Bt = __builtin_amdgcn_make_buffer_rsrc((void*)Bt, 0, 0x7fffffff, 0x00020000);
;   if (!pre) {
;     STAGE(SB(0, 0), Bt, bcol, 0); STAGE(SA(0, 0), A, brow, 0);
;     STAGE(SB(0, 1), Bt, bcol + HALF, 0); STAGE(SA(0, 1), A, brow + HALF, 0);
;   }
;   if (wr == 1) BAR;
;   if (pre) { WAIT_V(0); } else { WAIT_V(4); }
;   BAR;
;   STAGE(SB(1, 0), Bt, bcol, 1); STAGE(SA(1, 0), A, brow, 1); STAGE(SB(1, 1), Bt, bcol + HALF, 1);
;   WAIT_V(6); BAR;
.LBB0_1926:
	v_readlane_b32 s25, v254, 30
	s_lshl_b32 s16, s20, 11
	s_or_b32 s10, s16, 0x80
	v_add_u32_e32 v146, s25, v0
	v_add_u32_e32 v147, 0x2000, v146
	v_readfirstlane_b32 s11, v146
	s_mov_b32 m0, s11
	v_readfirstlane_b32 s11, v147
	v_add_u32_e32 v148, 0x8000, v136
	s_barrier
	buffer_load_dwordx4 v32, s[76:79], s10 offen lds
	s_mov_b32 m0, s11
	s_lshl_b32 s17, s19, 11
	v_readfirstlane_b32 s24, v148
	v_add_u32_e32 v150, 0xa000, v136
	v_readlane_b32 s26, v254, 31
	buffer_load_dwordx4 v131, s[76:79], s10 offen lds
	s_or_b32 s23, s17, 0x80
	s_mov_b32 s10, s78
	s_mov_b32 s11, s79
	s_mov_b32 m0, s24
	v_readfirstlane_b32 s24, v150
	v_add_u32_e32 v153, s26, v0
	buffer_load_dwordx4 v32, s[8:11], s23 offen lds
	s_mov_b32 m0, s24
	v_readfirstlane_b32 s24, v153
	v_add_u32_e32 v154, 0x2000, v153
	buffer_load_dwordx4 v131, s[8:11], s23 offen lds
	s_add_i32 s23, s16, 0x40080
	s_mov_b32 m0, s24
	v_readfirstlane_b32 s24, v154
	buffer_load_dwordx4 v32, s[76:79], s23 offen lds
	s_mov_b32 m0, s24
	v_and_b32_e32 v2, 15, v130
	buffer_load_dwordx4 v131, s[76:79], s23 offen lds
	v_lshlrev_b32_e32 v0, 6, v2
	v_lshlrev_b32_e32 v2, 2, v130
	v_and_b32_e32 v3, 48, v130
	v_and_b32_e32 v2, 32, v2
	v_bitop3_b32 v0, v0, v2, v3 bitop3:0x36
	s_waitcnt vmcnt(11)
	v_lshlrev_b32_e32 v8, 6, v130
	s_movk_i32 s23, 0x3c0
	s_waitcnt vmcnt(6)
	v_add_u32_e32 v4, s71, v0
	v_add_u32_e32 v5, s73, v0
	v_add_u32_e32 v6, s25, v0
	v_add_u32_e32 v7, s26, v0
	v_lshlrev_b32_e32 v1, 13, v1
	v_add_u32_e32 v10, 0, v0
	v_and_or_b32 v0, v8, s23, v3
	v_and_b32_e32 v9, 0x3000, v8
	v_xad_u32 v2, v0, v2, 0
	v_or_b32_e32 v3, 0x800, v1
	v_or_b32_e32 v8, 0x1000, v1
	v_or_b32_e32 v11, 0x1800, v1
	v_mov_b32_e32 v0, 0
	v_add_u32_e32 v152, 0xc000, v136
	v_add_u32_e32 v151, 0xe000, v136
	v_add_u32_e32 v139, 0x2000, v137
	v_add_u32_e32 v138, 0x2000, v134
	s_mov_b32 s23, -2
	s_mov_b32 s24, 0
	v_add_u32_e32 v155, v4, v9
	v_add_u32_e32 v143, v10, v1
	v_add_u32_e32 v142, v2, v3
	v_add_u32_e32 v141, v2, v8
	v_add_u32_e32 v140, v2, v11
	v_add_u32_e32 v149, v5, v9
	v_add_u32_e32 v145, v6, v9
	v_add_u32_e32 v144, v7, v9
	v_mov_b32_e32 v1, v0
	v_mov_b64_e32 v[2:3], 0
	v_mov_b64_e32 v[4:5], 0
	v_mov_b64_e32 v[6:7], 0
	v_mov_b64_e32 v[8:9], 0
	v_mov_b64_e32 v[10:11], 0
	s_waitcnt vmcnt(10)
	v_mov_b64_e32 v[12:13], 0
	v_mov_b64_e32 v[14:15], 0
	v_mov_b64_e32 v[16:17], 0
	v_mov_b64_e32 v[18:19], 0
	v_mov_b64_e32 v[20:21], 0
	v_mov_b64_e32 v[22:23], 0
	v_mov_b64_e32 v[24:25], 0
	v_mov_b64_e32 v[26:27], 0
	v_mov_b64_e32 v[28:29], 0
	v_mov_b64_e32 v[30:31], 0
	v_mov_b64_e32 v[34:35], 0
	v_mov_b64_e32 v[36:37], 0
	v_mov_b64_e32 v[38:39], 0
	v_mov_b64_e32 v[40:41], 0
	v_mov_b64_e32 v[42:43], 0
	v_mov_b64_e32 v[44:45], 0
	v_mov_b64_e32 v[46:47], 0
	v_mov_b64_e32 v[48:49], 0
	v_mov_b64_e32 v[50:51], 0
	v_mov_b64_e32 v[52:53], 0
	v_mov_b64_e32 v[54:55], 0
	v_mov_b64_e32 v[56:57], 0
	v_mov_b64_e32 v[58:59], 0
	v_mov_b64_e32 v[60:61], 0
	v_mov_b64_e32 v[62:63], 0
	v_mov_b64_e32 v[64:65], 0
	v_mov_b64_e32 v[66:67], 0
	v_mov_b64_e32 v[68:69], 0
	v_mov_b64_e32 v[70:71], 0
	v_mov_b64_e32 v[72:73], 0
	v_mov_b64_e32 v[74:75], 0
	v_mov_b64_e32 v[76:77], 0
	v_mov_b64_e32 v[78:79], 0
	v_mov_b64_e32 v[80:81], 0
	v_mov_b64_e32 v[82:83], 0
	v_mov_b64_e32 v[84:85], 0
	v_mov_b64_e32 v[86:87], 0
	v_mov_b64_e32 v[88:89], 0
	v_mov_b64_e32 v[90:91], 0
	v_mov_b64_e32 v[92:93], 0
	v_mov_b64_e32 v[94:95], 0
	v_mov_b64_e32 v[96:97], 0
	v_mov_b64_e32 v[98:99], 0
	v_mov_b64_e32 v[100:101], 0
	v_mov_b64_e32 v[102:103], 0
	v_mov_b64_e32 v[104:105], 0
	v_mov_b64_e32 v[106:107], 0
	v_mov_b64_e32 v[108:109], 0
	v_mov_b64_e32 v[110:111], 0
	v_mov_b64_e32 v[112:113], 0
	v_mov_b64_e32 v[114:115], 0
	v_mov_b64_e32 v[116:117], 0
	v_mov_b64_e32 v[118:119], 0
	v_mov_b64_e32 v[120:121], 0
	v_mov_b64_e32 v[122:123], 0
	v_mov_b64_e32 v[124:125], 0
	v_mov_b64_e32 v[126:127], 0
	v_mov_b64_e32 v[128:129], 0
	s_barrier

; #define STAGE(P, BASE, br, kt) do { int _so = ((br) * K + (kt) * BK) * 2; \
;     __builtin_amdgcn_raw_ptr_buffer_load_lds(rs_##BASE, (__attribute__((address_space(3))) void*)((char*)(P) + tx * 16), 16, voff0, _so, 0, 0); \
;     __builtin_amdgcn_raw_ptr_buffer_load_lds(rs_##BASE, (__attribute__((address_space(3))) void*)((char*)(P) + tx * 16 + 8192), 16, voff1, _so, 0, 0); } while (0)
; #define WAIT_V(n) asm volatile("s_waitcnt vmcnt(" #n ")" ::: "memory")
; #define BAR __builtin_amdgcn_s_barrier()
; template <class Epi> ...
;     ...
;   int wid = tx >> 6, lane = tx & 63, wr = wid >> 2, wc = wid & 3, fr = lane & 15, fq = lane >> 4;
;   f32x4 acc[2][2][4][2] = {};
;   bf16x8 At[4][2], B0[2][2], B1[2][2];
;   int nt = K / BK;
;   int voff0, voff1;
;   { int _r, _c; stage_rc(tx * 16, _r, _c); voff0 = (_r * K + _c) * 2; stage_rc(tx * 16 + 8192, _r, _c); voff1 = (_r * K + _c) * 2; }
;   __amdgpu_buffer_rsrc_t rs_A = __builtin_amdgcn_make_buffer_rsrc((void*)A, 0, 0x7fffffff, 0x00020000);
;   __amdgpu_buffer_rsrc_t rs_Bt = __builtin_amdgcn_make_buffer_rsrc((void*)Bt, 0, 0x7fffffff, 0x00020000);
;   if (!pre) {
;     STAGE(SB(0, 0), Bt, bcol, 0); STAGE(SA(0, 0), A, brow, 0);
;     STAGE(SB(0, 1), Bt, bcol + HALF, 0); STAGE(SA(0, 1), A, brow + HALF, 0);
;   }
;   if (wr == 1) BAR;
;   if (pre) { WAIT_V(0); } else { WAIT_V(4); }
;   BAR;
;   STAGE(SB(1, 0), Bt, bcol, 1); STAGE(SA(1, 0), A, brow, 1); STAGE(SB(1, 1), Bt, bcol + HALF, 1);
;   WAIT_V(6); BAR;
.LBB0_2252:
	v_readlane_b32 s25, v254, 30
	s_lshl_b32 s16, s19, 11
	s_or_b32 s10, s16, 0x80
	v_add_u32_e32 v146, s25, v0
	v_add_u32_e32 v147, 0x2000, v146
	v_readfirstlane_b32 s11, v146
	s_mov_b32 m0, s11
	v_readfirstlane_b32 s11, v147
	v_add_u32_e32 v148, 0x8000, v136
	s_barrier
	buffer_load_dwordx4 v32, s[76:79], s10 offen lds
	s_mov_b32 m0, s11
	s_lshl_b32 s17, s20, 11
	v_readfirstlane_b32 s24, v148
	v_add_u32_e32 v150, 0xa000, v136
	v_readlane_b32 s26, v254, 31
	buffer_load_dwordx4 v131, s[76:79], s10 offen lds
	s_or_b32 s23, s17, 0x80
	s_mov_b32 s10, s78
	s_mov_b32 s11, s79
	s_mov_b32 m0, s24
	v_readfirstlane_b32 s24, v150
	v_add_u32_e32 v153, s26, v0
	buffer_load_dwordx4 v32, s[8:11], s23 offen lds
	s_mov_b32 m0, s24
	v_readfirstlane_b32 s24, v153
	v_add_u32_e32 v154, 0x2000, v153
	buffer_load_dwordx4 v131, s[8:11], s23 offen lds
	s_add_i32 s23, s16, 0x40080
	s_mov_b32 m0, s24
	v_readfirstlane_b32 s24, v154
	buffer_load_dwordx4 v32, s[76:79], s23 offen lds
	s_mov_b32 m0, s24
	v_and_b32_e32 v2, 15, v130
	buffer_load_dwordx4 v131, s[76:79], s23 offen lds
	v_lshlrev_b32_e32 v0, 6, v2
	v_lshlrev_b32_e32 v2, 2, v130
	v_and_b32_e32 v3, 48, v130
	v_and_b32_e32 v2, 32, v2
	v_bitop3_b32 v0, v0, v2, v3 bitop3:0x36
	s_waitcnt vmcnt(11)
	v_lshlrev_b32_e32 v8, 6, v130
	s_movk_i32 s23, 0x3c0
	s_waitcnt vmcnt(6)
	v_add_u32_e32 v4, s71, v0
	v_add_u32_e32 v5, s73, v0
	v_add_u32_e32 v6, s25, v0
	v_add_u32_e32 v7, s26, v0
	v_lshlrev_b32_e32 v1, 13, v1
	v_add_u32_e32 v10, 0, v0
	v_and_or_b32 v0, v8, s23, v3
	v_and_b32_e32 v9, 0x3000, v8
	v_xad_u32 v2, v0, v2, 0
	v_or_b32_e32 v3, 0x800, v1
	v_or_b32_e32 v8, 0x1000, v1
	v_or_b32_e32 v11, 0x1800, v1
	v_mov_b32_e32 v0, 0
	v_add_u32_e32 v152, 0xc000, v136
	v_add_u32_e32 v151, 0xe000, v136
	v_add_u32_e32 v139, 0x2000, v137
	v_add_u32_e32 v138, 0x2000, v134
	s_mov_b32 s23, -2
	s_mov_b32 s24, 0
	v_add_u32_e32 v155, v4, v9
	v_add_u32_e32 v143, v10, v1
	v_add_u32_e32 v142, v2, v3
	v_add_u32_e32 v141, v2, v8
	v_add_u32_e32 v140, v2, v11
	v_add_u32_e32 v149, v5, v9
	v_add_u32_e32 v145, v6, v9
	v_add_u32_e32 v144, v7, v9
	v_mov_b32_e32 v1, v0
	v_mov_b64_e32 v[2:3], 0
	v_mov_b64_e32 v[4:5], 0
	v_mov_b64_e32 v[6:7], 0
	v_mov_b64_e32 v[8:9], 0
	v_mov_b64_e32 v[10:11], 0
	s_waitcnt vmcnt(10)
	v_mov_b64_e32 v[12:13], 0
	v_mov_b64_e32 v[14:15], 0
	v_mov_b64_e32 v[16:17], 0
	v_mov_b64_e32 v[18:19], 0
	v_mov_b64_e32 v[20:21], 0
	v_mov_b64_e32 v[22:23], 0
	v_mov_b64_e32 v[24:25], 0
	v_mov_b64_e32 v[26:27], 0
	v_mov_b64_e32 v[28:29], 0
	v_mov_b64_e32 v[30:31], 0
	v_mov_b64_e32 v[34:35], 0
	v_mov_b64_e32 v[36:37], 0
	v_mov_b64_e32 v[38:39], 0
	v_mov_b64_e32 v[40:41], 0
	v_mov_b64_e32 v[42:43], 0
	v_mov_b64_e32 v[44:45], 0
	v_mov_b64_e32 v[46:47], 0
	v_mov_b64_e32 v[48:49], 0
	v_mov_b64_e32 v[50:51], 0
	v_mov_b64_e32 v[52:53], 0
	v_mov_b64_e32 v[54:55], 0
	v_mov_b64_e32 v[56:57], 0
	v_mov_b64_e32 v[58:59], 0
	v_mov_b64_e32 v[60:61], 0
	v_mov_b64_e32 v[62:63], 0
	v_mov_b64_e32 v[64:65], 0
	v_mov_b64_e32 v[66:67], 0
	v_mov_b64_e32 v[68:69], 0
	v_mov_b64_e32 v[70:71], 0
	v_mov_b64_e32 v[72:73], 0
	v_mov_b64_e32 v[74:75], 0
	v_mov_b64_e32 v[76:77], 0
	v_mov_b64_e32 v[78:79], 0
	v_mov_b64_e32 v[80:81], 0
	v_mov_b64_e32 v[82:83], 0
	v_mov_b64_e32 v[84:85], 0
	v_mov_b64_e32 v[86:87], 0
	v_mov_b64_e32 v[88:89], 0
	v_mov_b64_e32 v[90:91], 0
	v_mov_b64_e32 v[92:93], 0
	v_mov_b64_e32 v[94:95], 0
	v_mov_b64_e32 v[96:97], 0
	v_mov_b64_e32 v[98:99], 0
	v_mov_b64_e32 v[100:101], 0
	v_mov_b64_e32 v[102:103], 0
	v_mov_b64_e32 v[104:105], 0
	v_mov_b64_e32 v[106:107], 0
	v_mov_b64_e32 v[108:109], 0
	v_mov_b64_e32 v[110:111], 0
	v_mov_b64_e32 v[112:113], 0
	v_mov_b64_e32 v[114:115], 0
	v_mov_b64_e32 v[116:117], 0
	v_mov_b64_e32 v[118:119], 0
	v_mov_b64_e32 v[120:121], 0
	v_mov_b64_e32 v[122:123], 0
	v_mov_b64_e32 v[124:125], 0
	v_mov_b64_e32 v[126:127], 0
	v_mov_b64_e32 v[128:129], 0
	s_barrier

; #define STAGE(P, BASE, br, kt) do { int _so = ((br) * K + (kt) * BK) * 2; \
;     __builtin_amdgcn_raw_ptr_buffer_load_lds(rs_##BASE, (__attribute__((address_space(3))) void*)((char*)(P) + tx * 16), 16, voff0, _so, 0, 0); \
;     __builtin_amdgcn_raw_ptr_buffer_load_lds(rs_##BASE, (__attribute__((address_space(3))) void*)((char*)(P) + tx * 16 + 8192), 16, voff1, _so, 0, 0); } while (0)
; #define WAIT_V(n) asm volatile("s_waitcnt vmcnt(" #n ")" ::: "memory")
; #define BAR __builtin_amdgcn_s_barrier()
; template <class Epi> ...
;     ...
;   int wid = tx >> 6, lane = tx & 63, wr = wid >> 2, wc = wid & 3, fr = lane & 15, fq = lane >> 4;
;   f32x4 acc[2][2][4][2] = {};
;   bf16x8 At[4][2], B0[2][2], B1[2][2];
;   int nt = K / BK;
;   int voff0, voff1;
;   { int _r, _c; stage_rc(tx * 16, _r, _c); voff0 = (_r * K + _c) * 2; stage_rc(tx * 16 + 8192, _r, _c); voff1 = (_r * K + _c) * 2; }
;   __amdgpu_buffer_rsrc_t rs_A = __builtin_amdgcn_make_buffer_rsrc((void*)A, 0, 0x7fffffff, 0x00020000);
;   __amdgpu_buffer_rsrc_t rs_Bt = __builtin_amdgcn_make_buffer_rsrc((void*)Bt, 0, 0x7fffffff, 0x00020000);
;   if (!pre) {
;     STAGE(SB(0, 0), Bt, bcol, 0); STAGE(SA(0, 0), A, brow, 0);
;     STAGE(SB(0, 1), Bt, bcol + HALF, 0); STAGE(SA(0, 1), A, brow + HALF, 0);
;   }
;   if (wr == 1) BAR;
;   if (pre) { WAIT_V(0); } else { WAIT_V(4); }
;   BAR;
;   STAGE(SB(1, 0), Bt, bcol, 1); STAGE(SA(1, 0), A, brow, 1); STAGE(SB(1, 1), Bt, bcol + HALF, 1);
;   WAIT_V(6); BAR;
.LBB0_2335:
	v_readlane_b32 s23, v254, 30
	s_or_b32 s6, s22, 0x80
	v_add_u32_e32 v148, 0x8000, v136
	v_add_u32_e32 v146, s23, v0
	v_add_u32_e32 v147, 0x2000, v146
	v_readfirstlane_b32 s7, v146
	s_mov_b32 m0, s7
	v_readfirstlane_b32 s7, v147
	s_barrier
	buffer_load_dwordx4 v32, s[76:79], s6 offen lds
	s_mov_b32 m0, s7
	v_readfirstlane_b32 s15, v148
	v_add_u32_e32 v150, 0xa000, v136
	v_readlane_b32 s24, v254, 31
	buffer_load_dwordx4 v131, s[76:79], s6 offen lds
	s_or_b32 s14, s21, 0x80
	s_mov_b32 s6, s78
	s_mov_b32 s7, s79
	s_mov_b32 m0, s15
	v_readfirstlane_b32 s15, v150
	v_add_u32_e32 v153, s24, v0
	buffer_load_dwordx4 v32, s[4:7], s14 offen lds
	s_mov_b32 m0, s15
	v_readfirstlane_b32 s15, v153
	v_add_u32_e32 v154, 0x2000, v153
	buffer_load_dwordx4 v131, s[4:7], s14 offen lds
	s_add_i32 s14, s22, 0xb0080
	s_mov_b32 m0, s15
	v_readfirstlane_b32 s15, v154
	buffer_load_dwordx4 v32, s[76:79], s14 offen lds
	s_mov_b32 m0, s15
	v_and_b32_e32 v2, 15, v130
	buffer_load_dwordx4 v131, s[76:79], s14 offen lds
	v_lshlrev_b32_e32 v0, 6, v2
	v_lshlrev_b32_e32 v2, 2, v130
	v_and_b32_e32 v3, 48, v130
	v_and_b32_e32 v2, 32, v2
	v_bitop3_b32 v0, v0, v2, v3 bitop3:0x36
	s_waitcnt vmcnt(11)
	v_lshlrev_b32_e32 v8, 6, v130
	s_movk_i32 s14, 0x3c0
	s_waitcnt vmcnt(6)
	v_add_u32_e32 v4, s71, v0
	v_add_u32_e32 v5, s73, v0
	v_add_u32_e32 v6, s23, v0
	v_add_u32_e32 v7, s24, v0
	v_lshlrev_b32_e32 v1, 13, v1
	v_add_u32_e32 v10, 0, v0
	v_and_or_b32 v0, v8, s14, v3
	v_and_b32_e32 v9, 0x3000, v8
	v_xad_u32 v2, v0, v2, 0
	v_or_b32_e32 v3, 0x800, v1
	v_or_b32_e32 v8, 0x1000, v1
	v_or_b32_e32 v11, 0x1800, v1
	v_mov_b32_e32 v0, 0
	v_add_u32_e32 v152, 0xc000, v136
	v_add_u32_e32 v151, 0xe000, v136
	v_add_u32_e32 v139, 0x2000, v137
	v_add_u32_e32 v138, 0x2000, v134
	s_mov_b32 s14, -2
	s_mov_b32 s15, 0
	v_add_u32_e32 v155, v4, v9
	v_add_u32_e32 v143, v10, v1
	v_add_u32_e32 v142, v2, v3
	v_add_u32_e32 v141, v2, v8
	v_add_u32_e32 v140, v2, v11
	v_add_u32_e32 v149, v5, v9
	v_add_u32_e32 v145, v6, v9
	v_add_u32_e32 v144, v7, v9
	v_mov_b32_e32 v1, v0
	v_mov_b64_e32 v[2:3], 0
	v_mov_b64_e32 v[4:5], 0
	v_mov_b64_e32 v[6:7], 0
	v_mov_b64_e32 v[8:9], 0
	v_mov_b64_e32 v[10:11], 0
	s_waitcnt vmcnt(10)
	v_mov_b64_e32 v[12:13], 0
	v_mov_b64_e32 v[14:15], 0
	v_mov_b64_e32 v[16:17], 0
	v_mov_b64_e32 v[18:19], 0
	v_mov_b64_e32 v[20:21], 0
	v_mov_b64_e32 v[22:23], 0
	v_mov_b64_e32 v[24:25], 0
	v_mov_b64_e32 v[26:27], 0
	v_mov_b64_e32 v[28:29], 0
	v_mov_b64_e32 v[30:31], 0
	v_mov_b64_e32 v[34:35], 0
	v_mov_b64_e32 v[36:37], 0
	v_mov_b64_e32 v[38:39], 0
	v_mov_b64_e32 v[40:41], 0
	v_mov_b64_e32 v[42:43], 0
	v_mov_b64_e32 v[44:45], 0
	v_mov_b64_e32 v[46:47], 0
	v_mov_b64_e32 v[48:49], 0
	v_mov_b64_e32 v[50:51], 0
	v_mov_b64_e32 v[52:53], 0
	v_mov_b64_e32 v[54:55], 0
	v_mov_b64_e32 v[56:57], 0
	v_mov_b64_e32 v[58:59], 0
	v_mov_b64_e32 v[60:61], 0
	v_mov_b64_e32 v[62:63], 0
	v_mov_b64_e32 v[64:65], 0
	v_mov_b64_e32 v[66:67], 0
	v_mov_b64_e32 v[68:69], 0
	v_mov_b64_e32 v[70:71], 0
	v_mov_b64_e32 v[72:73], 0
	v_mov_b64_e32 v[74:75], 0
	v_mov_b64_e32 v[76:77], 0
	v_mov_b64_e32 v[78:79], 0
	v_mov_b64_e32 v[80:81], 0
	v_mov_b64_e32 v[82:83], 0
	v_mov_b64_e32 v[84:85], 0
	v_mov_b64_e32 v[86:87], 0
	v_mov_b64_e32 v[88:89], 0
	v_mov_b64_e32 v[90:91], 0
	v_mov_b64_e32 v[92:93], 0
	v_mov_b64_e32 v[94:95], 0
	v_mov_b64_e32 v[96:97], 0
	v_mov_b64_e32 v[98:99], 0
	v_mov_b64_e32 v[100:101], 0
	v_mov_b64_e32 v[102:103], 0
	v_mov_b64_e32 v[104:105], 0
	v_mov_b64_e32 v[106:107], 0
	v_mov_b64_e32 v[108:109], 0
	v_mov_b64_e32 v[110:111], 0
	v_mov_b64_e32 v[112:113], 0
	v_mov_b64_e32 v[114:115], 0
	v_mov_b64_e32 v[116:117], 0
	v_mov_b64_e32 v[118:119], 0
	v_mov_b64_e32 v[120:121], 0
	v_mov_b64_e32 v[122:123], 0
	v_mov_b64_e32 v[124:125], 0
	v_mov_b64_e32 v[126:127], 0
	v_mov_b64_e32 v[128:129], 0
	s_barrier
